# FIN phase rewritten again: each sample row split over the 8 waves of its workgroup (36 x 1 KiB loads in flight per wave, slabs added in slab order, per-wave sums of squares combined through LDS), on t
# speedup vs baseline: 1.0063x; 1.0063x over previous
.LBB0_1050:
	s_or_b64 exec, exec, s[0:1]
	v_mov_b32_e32 v1, v0
	v_readlane_b32 s0, v253, 12
	v_readlane_b32 s2, v253, 51
	v_readlane_b32 s1, v253, 10
	s_waitcnt lgkmcnt(0)
	s_barrier
	s_mov_b64 s[10:11], s[84:85]
	s_cmpk_gt_i32 s0, 0xff
	s_cbranch_scc1 .LBB0_1062
	v_and_b32_e32 v1, 63, v1
	v_readlane_b32 s36, v254, 26
	v_readlane_b32 s37, v254, 27
	v_readlane_b32 s38, v253, 37
	v_readlane_b32 s39, v253, 38
	v_readlane_b32 s40, v254, 11
	v_readlane_b32 s41, v254, 12
	v_readlane_b32 s42, v254, 9
	v_readlane_b32 s43, v254, 10
	v_readlane_b32 s44, v253, 10
	v_lshlrev_b32_e32 v2, 4, v1
	s_lshl_b32 s3, s2, 11
	s_lshl_b32 s46, s2, 2
	s_nop 1
	v_add_u32_e32 v2, s3, v2
	v_lshrrev_b32_e32 v3, 1, v2
	v_mov_b32_e32 v5, 0
.Lfin8_row:
	s_mov_b32 s1, 0
	s_lshl_b64 s[12:13], s[0:1], 14
	s_add_u32 s8, s10, 0x4979c000
	s_addc_u32 s9, s11, 0
	s_and_b64 s[14:15], s[36:37], exec
	s_cselect_b32 s14, s8, s38
	s_cselect_b32 s15, s9, s39
	s_cselect_b32 s16, s40, s8
	s_cselect_b32 s17, s41, s9
	s_add_u32 s14, s14, s12
	s_addc_u32 s15, s15, s13
	s_add_u32 s16, s16, s12
	s_addc_u32 s17, s17, s13
	s_add_u32 s18, s10, 0x49c1d000
	s_addc_u32 s19, s11, 0
	s_add_u32 s18, s18, s12
	s_addc_u32 s19, s19, s13
	global_load_dwordx4 v[6:9], v2, s[14:15]
	global_load_dwordx4 v[10:13], v2, s[14:15] offset:1024
	global_load_dwordx4 v[14:17], v2, s[18:19]
	global_load_dwordx4 v[18:21], v2, s[18:19] offset:1024
	s_add_u32 s18, s18, 0x400000
	s_addc_u32 s19, s19, 0
	global_load_dwordx4 v[22:25], v2, s[18:19]
	global_load_dwordx4 v[26:29], v2, s[18:19] offset:1024
	s_add_u32 s18, s18, 0x400000
	s_addc_u32 s19, s19, 0
	global_load_dwordx4 v[30:33], v2, s[18:19]
	global_load_dwordx4 v[34:37], v2, s[18:19] offset:1024
	s_add_u32 s18, s18, 0x400000
	s_addc_u32 s19, s19, 0
	global_load_dwordx4 v[38:41], v2, s[18:19]
	global_load_dwordx4 v[42:45], v2, s[18:19] offset:1024
	s_add_u32 s18, s18, 0x400000
	s_addc_u32 s19, s19, 0
	global_load_dwordx4 v[46:49], v2, s[18:19]
	global_load_dwordx4 v[50:53], v2, s[18:19] offset:1024
	s_add_u32 s18, s18, 0x400000
	s_addc_u32 s19, s19, 0
	global_load_dwordx4 v[54:57], v2, s[18:19]
	global_load_dwordx4 v[58:61], v2, s[18:19] offset:1024
	s_add_u32 s18, s18, 0x400000
	s_addc_u32 s19, s19, 0
	global_load_dwordx4 v[62:65], v2, s[18:19]
	global_load_dwordx4 v[66:69], v2, s[18:19] offset:1024
	s_add_u32 s18, s18, 0x400000
	s_addc_u32 s19, s19, 0
	global_load_dwordx4 v[70:73], v2, s[18:19]
	global_load_dwordx4 v[74:77], v2, s[18:19] offset:1024
	s_add_u32 s18, s18, 0x400000
	s_addc_u32 s19, s19, 0
	global_load_dwordx4 v[78:81], v2, s[18:19]
	global_load_dwordx4 v[82:85], v2, s[18:19] offset:1024
	s_add_u32 s18, s18, 0x400000
	s_addc_u32 s19, s19, 0
	global_load_dwordx4 v[86:89], v2, s[18:19]
	global_load_dwordx4 v[90:93], v2, s[18:19] offset:1024
	s_add_u32 s18, s18, 0x400000
	s_addc_u32 s19, s19, 0
	global_load_dwordx4 v[94:97], v2, s[18:19]
	global_load_dwordx4 v[98:101], v2, s[18:19] offset:1024
	s_add_u32 s18, s18, 0x400000
	s_addc_u32 s19, s19, 0
	global_load_dwordx4 v[102:105], v2, s[18:19]
	global_load_dwordx4 v[106:109], v2, s[18:19] offset:1024
	s_add_u32 s18, s18, 0x400000
	s_addc_u32 s19, s19, 0
	global_load_dwordx4 v[110:113], v2, s[18:19]
	global_load_dwordx4 v[114:117], v2, s[18:19] offset:1024
	s_add_u32 s18, s18, 0x400000
	s_addc_u32 s19, s19, 0
	global_load_dwordx4 v[118:121], v2, s[18:19]
	global_load_dwordx4 v[122:125], v2, s[18:19] offset:1024
	s_add_u32 s18, s18, 0x400000
	s_addc_u32 s19, s19, 0
	global_load_dwordx4 v[126:129], v2, s[18:19]
	global_load_dwordx4 v[130:133], v2, s[18:19] offset:1024
	s_add_u32 s18, s18, 0x400000
	s_addc_u32 s19, s19, 0
	global_load_dwordx4 v[134:137], v2, s[18:19]
	global_load_dwordx4 v[138:141], v2, s[18:19] offset:1024
	global_load_dwordx4 v[142:145], v2, s[42:43]
	global_load_dwordx4 v[146:149], v2, s[42:43] offset:1024
	s_waitcnt vmcnt(34)
	s_waitcnt vmcnt(32)
	v_pk_add_f32 v[6:7], v[6:7], v[14:15]
	v_pk_add_f32 v[8:9], v[8:9], v[16:17]
	v_pk_add_f32 v[10:11], v[10:11], v[18:19]
	v_pk_add_f32 v[12:13], v[12:13], v[20:21]
	s_waitcnt vmcnt(30)
	v_pk_add_f32 v[6:7], v[6:7], v[22:23]
	v_pk_add_f32 v[8:9], v[8:9], v[24:25]
	v_pk_add_f32 v[10:11], v[10:11], v[26:27]
	v_pk_add_f32 v[12:13], v[12:13], v[28:29]
	s_waitcnt vmcnt(28)
	v_pk_add_f32 v[6:7], v[6:7], v[30:31]
	v_pk_add_f32 v[8:9], v[8:9], v[32:33]
	v_pk_add_f32 v[10:11], v[10:11], v[34:35]
	v_pk_add_f32 v[12:13], v[12:13], v[36:37]
	s_waitcnt vmcnt(26)
	v_pk_add_f32 v[6:7], v[6:7], v[38:39]
	v_pk_add_f32 v[8:9], v[8:9], v[40:41]
	v_pk_add_f32 v[10:11], v[10:11], v[42:43]
	v_pk_add_f32 v[12:13], v[12:13], v[44:45]
	s_waitcnt vmcnt(24)
	v_pk_add_f32 v[6:7], v[6:7], v[46:47]
	v_pk_add_f32 v[8:9], v[8:9], v[48:49]
	v_pk_add_f32 v[10:11], v[10:11], v[50:51]
	v_pk_add_f32 v[12:13], v[12:13], v[52:53]
	s_waitcnt vmcnt(22)
	v_pk_add_f32 v[6:7], v[6:7], v[54:55]
	v_pk_add_f32 v[8:9], v[8:9], v[56:57]
	v_pk_add_f32 v[10:11], v[10:11], v[58:59]
	v_pk_add_f32 v[12:13], v[12:13], v[60:61]
	s_waitcnt vmcnt(20)
	v_pk_add_f32 v[6:7], v[6:7], v[62:63]
	v_pk_add_f32 v[8:9], v[8:9], v[64:65]
	v_pk_add_f32 v[10:11], v[10:11], v[66:67]
	v_pk_add_f32 v[12:13], v[12:13], v[68:69]
	s_waitcnt vmcnt(18)
	v_pk_add_f32 v[6:7], v[6:7], v[70:71]
	v_pk_add_f32 v[8:9], v[8:9], v[72:73]
	v_pk_add_f32 v[10:11], v[10:11], v[74:75]
	v_pk_add_f32 v[12:13], v[12:13], v[76:77]
	s_waitcnt vmcnt(16)
	v_pk_add_f32 v[6:7], v[6:7], v[78:79]
	v_pk_add_f32 v[8:9], v[8:9], v[80:81]
	v_pk_add_f32 v[10:11], v[10:11], v[82:83]
	v_pk_add_f32 v[12:13], v[12:13], v[84:85]
	s_waitcnt vmcnt(14)
	v_pk_add_f32 v[6:7], v[6:7], v[86:87]
	v_pk_add_f32 v[8:9], v[8:9], v[88:89]
	v_pk_add_f32 v[10:11], v[10:11], v[90:91]
	v_pk_add_f32 v[12:13], v[12:13], v[92:93]
	s_waitcnt vmcnt(12)
	v_pk_add_f32 v[6:7], v[6:7], v[94:95]
	v_pk_add_f32 v[8:9], v[8:9], v[96:97]
	v_pk_add_f32 v[10:11], v[10:11], v[98:99]
	v_pk_add_f32 v[12:13], v[12:13], v[100:101]
	s_waitcnt vmcnt(10)
	v_pk_add_f32 v[6:7], v[6:7], v[102:103]
	v_pk_add_f32 v[8:9], v[8:9], v[104:105]
	v_pk_add_f32 v[10:11], v[10:11], v[106:107]
	v_pk_add_f32 v[12:13], v[12:13], v[108:109]
	s_waitcnt vmcnt(8)
	v_pk_add_f32 v[6:7], v[6:7], v[110:111]
	v_pk_add_f32 v[8:9], v[8:9], v[112:113]
	v_pk_add_f32 v[10:11], v[10:11], v[114:115]
	v_pk_add_f32 v[12:13], v[12:13], v[116:117]
	s_waitcnt vmcnt(6)
	v_pk_add_f32 v[6:7], v[6:7], v[118:119]
	v_pk_add_f32 v[8:9], v[8:9], v[120:121]
	v_pk_add_f32 v[10:11], v[10:11], v[122:123]
	v_pk_add_f32 v[12:13], v[12:13], v[124:125]
	s_waitcnt vmcnt(4)
	v_pk_add_f32 v[6:7], v[6:7], v[126:127]
	v_pk_add_f32 v[8:9], v[8:9], v[128:129]
	v_pk_add_f32 v[10:11], v[10:11], v[130:131]
	v_pk_add_f32 v[12:13], v[12:13], v[132:133]
	s_waitcnt vmcnt(2)
	v_pk_add_f32 v[6:7], v[6:7], v[134:135]
	v_pk_add_f32 v[8:9], v[8:9], v[136:137]
	v_pk_add_f32 v[10:11], v[10:11], v[138:139]
	v_pk_add_f32 v[12:13], v[12:13], v[140:141]
	s_waitcnt vmcnt(0)
	global_store_dwordx4 v2, v[6:9], s[16:17]
	global_store_dwordx4 v2, v[10:13], s[16:17] offset:1024
	s_andn2_b64 vcc, exec, s[60:61]
	s_cbranch_vccnz .Lfin8_next
	s_lshl_b64 s[14:15], s[0:1], 13
	s_add_u32 s20, s10, 0x10f80000
	s_addc_u32 s21, s11, 0
	s_add_u32 s20, s20, s14
	s_addc_u32 s21, s21, s15
	s_add_u32 s20, s20, 0x4000000
	s_addc_u32 s21, s21, 0
	v_mul_f32_e32 v150, v7, v7
	v_mul_f32_e32 v151, v9, v9
	v_fmac_f32_e32 v150, v6, v6
	v_fmac_f32_e32 v151, v8, v8
	v_mul_f32_e32 v152, v11, v11
	v_mul_f32_e32 v153, v13, v13
	v_fmac_f32_e32 v152, v10, v10
	v_fmac_f32_e32 v153, v12, v12
	v_add_f32_e32 v150, v150, v151
	v_add_f32_e32 v152, v152, v153
	v_add_f32_e32 v150, v150, v152
	v_pk_mul_f32 v[142:143], v[6:7], v[142:143]
	v_pk_mul_f32 v[144:145], v[8:9], v[144:145]
	v_pk_mul_f32 v[146:147], v[10:11], v[146:147]
	v_pk_mul_f32 v[148:149], v[12:13], v[148:149]
	ds_swizzle_b32 v151, v150 offset:swizzle(SWAP,1)
	v_cvt_pk_bf16_f32 v142, v142, v143
	v_cvt_pk_bf16_f32 v143, v144, v145
	v_cvt_pk_bf16_f32 v146, v146, v147
	v_cvt_pk_bf16_f32 v147, v148, v149
	global_store_dwordx2 v3, v[142:143], s[20:21]
	global_store_dwordx2 v3, v[146:147], s[20:21] offset:512
	s_waitcnt lgkmcnt(0)
	v_add_f32_e32 v150, v150, v151
	ds_swizzle_b32 v151, v150 offset:swizzle(SWAP,2)
	s_waitcnt lgkmcnt(0)
	v_add_f32_e32 v150, v150, v151
	ds_swizzle_b32 v151, v150 offset:swizzle(SWAP,4)
	s_waitcnt lgkmcnt(0)
	v_add_f32_e32 v150, v150, v151
	ds_swizzle_b32 v151, v150 offset:swizzle(SWAP,8)
	s_waitcnt lgkmcnt(0)
	v_add_f32_e32 v150, v150, v151
	ds_swizzle_b32 v151, v150 offset:swizzle(SWAP,16)
	s_waitcnt lgkmcnt(0)
	v_add_f32_e32 v150, v150, v151
	v_mov_b32_e32 v151, v150
	s_nop 1
	v_permlane32_swap_b32_e32 v150, v151
	v_add_f32_e32 v150, v150, v151
	v_mov_b32_e32 v152, s46
	s_mov_b64 s[14:15], exec
	s_mov_b64 exec, 1
	s_nop 1
	ds_write_b32 v152, v150
	s_mov_b64 exec, s[14:15]
	s_waitcnt lgkmcnt(0)
	s_barrier
	s_cmp_lg_u32 s2, 0
	s_cbranch_scc1 .Lfin8_ssq_done
	ds_read_b128 v[152:155], v5
	ds_read_b128 v[156:159], v5 offset:16
	s_lshl_b32 s3, s0, 2
	s_add_u32 s20, s10, 0x20400
	s_addc_u32 s21, s11, 0
	s_add_u32 s20, s20, s3
	s_addc_u32 s21, s21, 0
	s_waitcnt lgkmcnt(0)
	v_add_f32_e32 v152, v152, v153
	v_add_f32_e32 v152, v152, v154
	v_add_f32_e32 v152, v152, v155
	v_add_f32_e32 v152, v152, v156
	v_add_f32_e32 v152, v152, v157
	v_add_f32_e32 v152, v152, v158
	v_add_f32_e32 v152, v152, v159
	s_mov_b64 s[14:15], exec
	s_mov_b64 exec, 1
	s_nop 1
	global_store_dword v5, v152, s[20:21]
	s_mov_b64 exec, s[14:15]

.Lfin8_next:
	s_add_i32 s0, s0, s44
	s_cmpk_lt_i32 s0, 0x100
	s_cbranch_scc1 .Lfin8_row
